# sgu_ln items: 4 head-group items of a chunk on one XCD
# baseline (speedup 1.0000x reference)
; DI int get_bid() { int b = blockIdx.x; asm volatile("" : "+s"(b)); return b; }
; DI void sgu_ln_items(const Params& p, int e, char* smem) {
;     ...
;   for (int it = get_bid(); it < 576; it += gridDim.x) {
;     const int c = it >> 2, gq = it & 3;
;     const int rowbase = c < 128 ? c * 128 : M_PROMPT + (c - 128) * 32;
;     const int nvalid = c < 128 ? 128 : 32;
;     __syncthreads();
.LBB0_317:
	s_and_b32 s98, s4, 7
	s_lshl_b32 s98, s98, 2
	s_bfe_u32 s99, s4, 0x20003
	s_or_b32 s98, s98, s99
	s_andn2_b32 s99, s4, 31
	s_or_b32 s98, s98, s99
	s_ashr_i32 s58, s98, 2
	s_lshl_b32 s6, s58, 5
	s_lshl_b32 s5, s58, 7
	s_add_i32 s7, s6, 0x3000
	s_cmpk_lt_i32 s58, 0x80
	s_cselect_b32 s6, 0x80, 32
	s_cselect_b32 s5, s5, s7
	s_mov_b32 s7, -8
	v_mov_b32_e32 v62, v101
	s_barrier
	s_branch .LBB0_319

; DI float bflo(unsigned u) { return __uint_as_float(u << 16); }
; DI float bfhi(unsigned u) { return __uint_as_float(u & 0xffff0000u); }
; DI void sgu_ln_items(const Params& p, int e, char* smem) {
;     ...
;     const int rr = tid >> 3, cc = tid & 7;
;     u32x4 ld[4][4];
; #pragma unroll
;     for (int sl = 0; sl < 4; ++sl)
; #pragma unroll
;       for (int i4 = 0; i4 < 4; ++i4) {
;         const int i = rr + 32 * i4;
;         const int ic = i < nvalid ? i : 0;
;         ld[sl][i4] = *(const u32x4*)(uv + (size_t)(rowbase + ic) * 2048 + 1024 + gq * 256 + sl * 64 + cc * 8);
;       }
; #pragma unroll
;     for (int sl = 0; sl < 4; ++sl) {
;       const int ch = gq * 256 + sl * 64 + cc * 8;
;       const float4 g0 = *(const float4*)(lg + ch), g1 = *(const float4*)(lg + ch + 4);
;       const float4 b0 = *(const float4*)(lb + ch), b1 = *(const float4*)(lb + ch + 4);
; #pragma unroll
;       for (int i4 = 0; i4 < 4; ++i4) {
;         const int i = rr + 32 * i4;
;         float o[8];
;         if (i < nvalid) {
;           const u32x4 q = ld[sl][i4];
;           const float2 ms = st[i];
;           o[0] = (bflo(q[0]) - ms.x) * ms.y * g0.x + b0.x; o[1] = (bfhi(q[0]) - ms.x) * ms.y * g0.y + b0.y;
;           o[2] = (bflo(q[1]) - ms.x) * ms.y * g0.z + b0.z; o[3] = (bfhi(q[1]) - ms.x) * ms.y * g0.w + b0.w;
;           o[4] = (bflo(q[2]) - ms.x) * ms.y * g1.x + b1.x; o[5] = (bfhi(q[2]) - ms.x) * ms.y * g1.y + b1.y;
;           o[6] = (bflo(q[3]) - ms.x) * ms.y * g1.z + b1.z; o[7] = (bfhi(q[3]) - ms.x) * ms.y * g1.w + b1.w;
;           if (c >= 128) {
;             float* dst = p.out + OUT_SGUV + ((size_t)(e * 16 + (c - 128)) * 32 + i) * 1024 + ch;
;             *(float4*)dst = make_float4(o[0], o[1], o[2], o[3]);
;             *(float4*)(dst + 4) = make_float4(o[4], o[5], o[6], o[7]);
;           }
.LBB0_335:
	v_cmp_gt_i32_e64 s[46:47], s6, v90
	v_cmp_gt_i32_e64 s[44:45], s6, v96
	v_cmp_gt_i32_e64 s[42:43], s6, v98
	v_cndmask_b32_e64 v2, 0, v90, s[46:47]
	s_waitcnt lgkmcnt(0)
	v_cndmask_b32_e64 v4, 0, v96, s[44:45]
	v_cndmask_b32_e64 v6, 0, v98, s[42:43]
	v_cmp_gt_i32_e64 s[40:41], s6, v100
	v_add_u32_e32 v2, s5, v2
	v_add_u32_e32 v4, s5, v4
	v_add_u32_e32 v6, s5, v6
	v_cndmask_b32_e64 v8, 0, v100, s[40:41]
	s_and_b32 s98, s4, 7
	s_lshl_b32 s98, s98, 2
	s_bfe_u32 s99, s4, 0x20003
	s_or_b32 s98, s98, s99
	s_andn2_b32 s99, s4, 31
	s_or_b32 s98, s98, s99
	s_lshl_b32 s7, s98, 8
	v_ashrrev_i32_e32 v3, 31, v2
	v_readlane_b32 s10, v252, 33
	v_ashrrev_i32_e32 v5, 31, v4
	v_ashrrev_i32_e32 v7, 31, v6
	v_add_u32_e32 v8, s5, v8
	s_and_b32 s34, s7, 0x300
	v_lshlrev_b64 v[2:3], 12, v[2:3]
	v_readlane_b32 s11, v252, 34
	v_lshlrev_b64 v[4:5], 12, v[4:5]
	v_lshlrev_b64 v[6:7], 12, v[6:7]
	v_ashrrev_i32_e32 v9, 31, v8
	v_lshl_add_u64 v[2:3], s[10:11], 0, v[2:3]
	s_lshl_b32 s8, s34, 1
	s_mov_b32 s9, s35
	v_lshl_add_u64 v[4:5], s[10:11], 0, v[4:5]
	v_lshl_add_u64 v[6:7], s[10:11], 0, v[6:7]
	v_lshlrev_b64 v[8:9], 12, v[8:9]
	v_lshl_add_u64 v[2:3], v[2:3], 0, s[8:9]
	v_lshl_add_u64 v[4:5], v[4:5], 0, s[8:9]
	v_lshlrev_b32_e32 v182, 1, v92
	v_lshl_add_u64 v[6:7], v[6:7], 0, s[8:9]
	v_lshl_add_u64 v[8:9], s[10:11], 0, v[8:9]
	v_lshl_add_u64 v[4:5], v[4:5], 0, v[182:183]
	v_lshl_add_u64 v[6:7], v[6:7], 0, v[182:183]
	v_lshl_add_u64 v[8:9], v[8:9], 0, s[8:9]
	v_lshl_add_u64 v[76:77], v[2:3], 0, v[182:183]
	s_barrier
	v_lshl_add_u64 v[54:55], v[8:9], 0, v[182:183]
	global_load_dwordx4 v[46:49], v[76:77], off offset:2176
	global_load_dwordx4 v[30:33], v[76:77], off offset:2304
	global_load_dwordx4 v[42:45], v[4:5], off offset:2176
	global_load_dwordx4 v[26:29], v[4:5], off offset:2304
	global_load_dwordx4 v[38:41], v[6:7], off offset:2176
	global_load_dwordx4 v[22:25], v[6:7], off offset:2304
	global_load_dwordx4 v[34:37], v[54:55], off offset:2176
	global_load_dwordx4 v[18:21], v[54:55], off offset:2304
	global_load_dwordx4 v[78:81], v[4:5], off offset:2048
	global_load_dwordx4 v[14:17], v[76:77], off offset:2432
	global_load_dwordx4 v[70:73], v[6:7], off offset:2048
	global_load_dwordx4 v[10:13], v[4:5], off offset:2432
	global_load_dwordx4 v[50:53], v[54:55], off offset:2048
	s_nop 0
	global_load_dwordx4 v[6:9], v[6:7], off offset:2432
	s_nop 0
	global_load_dwordx4 v[2:5], v[54:55], off offset:2432
	v_or_b32_e32 v135, s34, v92
	v_readlane_b32 s6, v252, 47
	v_lshlrev_b32_e32 v182, 2, v135
	v_readlane_b32 s7, v252, 48
	s_nop 4
	global_load_dwordx4 v[54:57], v182, s[6:7] offset:16
	global_load_dwordx4 v[62:65], v182, s[6:7]
	v_readlane_b32 s6, v252, 49
	v_readlane_b32 s7, v252, 50
	s_nop 4
	global_load_dwordx4 v[58:61], v182, s[6:7] offset:16
	global_load_dwordx4 v[66:69], v182, s[6:7]
	s_cmpk_gt_i32 s58, 0x7f
	s_cselect_b64 s[50:51], -1, 0
	s_add_i32 s6, s58, 0xffffff90
	s_mov_b32 s7, s35
	s_lshl_b64 s[48:49], s[6:7], 17
	v_mov_b32_e32 v74, 0
	v_mov_b32_e32 v86, 0
	v_mov_b32_e32 v87, 0
	v_mov_b32_e32 v88, 0
	v_mov_b32_e32 v89, 0
	v_mov_b32_e32 v82, 0
	v_mov_b32_e32 v83, 0
	v_mov_b32_e32 v84, 0
	v_mov_b32_e32 v85, 0
	s_and_saveexec_b64 s[52:53], s[46:47]
	s_cbranch_execz .LBB0_338
	global_load_dwordx4 v[82:85], v[76:77], off offset:2048
	ds_read_b64 v[76:77], v125
	s_andn2_b64 vcc, exec, s[50:51]
	s_waitcnt vmcnt(0)
	v_lshlrev_b32_e32 v86, 16, v82
	v_and_b32_e32 v87, 0xffff0000, v82
	v_lshlrev_b32_e32 v82, 16, v83
	v_and_b32_e32 v83, 0xffff0000, v83
	v_lshlrev_b32_e32 v88, 16, v84
	v_and_b32_e32 v89, 0xffff0000, v84
	v_lshlrev_b32_e32 v84, 16, v85
	v_and_b32_e32 v85, 0xffff0000, v85
	s_waitcnt lgkmcnt(0)
	v_pk_add_f32 v[86:87], v[86:87], v[76:77] op_sel_hi:[1,0] neg_lo:[0,1] neg_hi:[0,1]
	v_pk_add_f32 v[82:83], v[82:83], v[76:77] op_sel_hi:[1,0] neg_lo:[0,1] neg_hi:[0,1]
	v_pk_add_f32 v[88:89], v[88:89], v[76:77] op_sel_hi:[1,0] neg_lo:[0,1] neg_hi:[0,1]
	v_pk_add_f32 v[84:85], v[84:85], v[76:77] op_sel_hi:[1,0] neg_lo:[0,1] neg_hi:[0,1]
	v_pk_mul_f32 v[86:87], v[76:77], v[86:87] op_sel:[1,0]
	v_pk_mul_f32 v[82:83], v[76:77], v[82:83] op_sel:[1,0]
	v_pk_mul_f32 v[136:137], v[76:77], v[88:89] op_sel:[1,0]
	v_pk_mul_f32 v[76:77], v[76:77], v[84:85] op_sel:[1,0]
	v_pk_fma_f32 v[86:87], v[62:63], v[86:87], v[66:67]
	v_pk_fma_f32 v[88:89], v[64:65], v[82:83], v[68:69]
	v_pk_fma_f32 v[82:83], v[54:55], v[136:137], v[58:59]
	v_pk_fma_f32 v[84:85], v[56:57], v[76:77], v[60:61]
	s_cbranch_vccnz .LBB0_338
	v_lshl_add_u64 v[76:77], v[110:111], 0, s[48:49]
	v_lshl_add_u64 v[76:77], v[76:77], 0, v[182:183]
	global_store_dwordx4 v[76:77], v[86:89], off
	global_store_dwordx4 v[76:77], v[82:85], off offset:16

; DI int get_bid() { int b = blockIdx.x; asm volatile("" : "+s"(b)); return b; }
; DI void sgu_ln_items(const Params& p, int e, char* smem) {
;     ...
;   for (int it = get_bid(); it < 576; it += gridDim.x) {
;     const int c = it >> 2, gq = it & 3;
;     const int rowbase = c < 128 ? c * 128 : M_PROMPT + (c - 128) * 32;
;     const int nvalid = c < 128 ? 128 : 32;
;     __syncthreads();
.LBB0_1165:
	s_and_b32 s98, s4, 7
	s_lshl_b32 s98, s98, 2
	s_bfe_u32 s99, s4, 0x20003
	s_or_b32 s98, s98, s99
	s_andn2_b32 s99, s4, 31
	s_or_b32 s98, s98, s99
	s_ashr_i32 s60, s98, 2
	s_lshl_b32 s6, s60, 5
	s_lshl_b32 s5, s60, 7
	s_add_i32 s7, s6, 0x3000
	s_cmpk_lt_i32 s60, 0x80
	s_cselect_b32 s6, 0x80, 32
	s_cselect_b32 s5, s5, s7
	s_mov_b32 s7, -8
	v_mov_b32_e32 v60, v97
	s_waitcnt lgkmcnt(0)
	s_barrier
	s_branch .LBB0_1167

; DI float bflo(unsigned u) { return __uint_as_float(u << 16); }
; DI float bfhi(unsigned u) { return __uint_as_float(u & 0xffff0000u); }
; DI void sgu_ln_items(const Params& p, int e, char* smem) {
;     ...
;     const int rr = tid >> 3, cc = tid & 7;
;     u32x4 ld[4][4];
; #pragma unroll
;     for (int sl = 0; sl < 4; ++sl)
; #pragma unroll
;       for (int i4 = 0; i4 < 4; ++i4) {
;         const int i = rr + 32 * i4;
;         const int ic = i < nvalid ? i : 0;
;         ld[sl][i4] = *(const u32x4*)(uv + (size_t)(rowbase + ic) * 2048 + 1024 + gq * 256 + sl * 64 + cc * 8);
;       }
; #pragma unroll
;     for (int sl = 0; sl < 4; ++sl) {
;       const int ch = gq * 256 + sl * 64 + cc * 8;
;       const float4 g0 = *(const float4*)(lg + ch), g1 = *(const float4*)(lg + ch + 4);
;       const float4 b0 = *(const float4*)(lb + ch), b1 = *(const float4*)(lb + ch + 4);
; #pragma unroll
;       for (int i4 = 0; i4 < 4; ++i4) {
;         const int i = rr + 32 * i4;
;         float o[8];
;         if (i < nvalid) {
;           const u32x4 q = ld[sl][i4];
;           const float2 ms = st[i];
;           o[0] = (bflo(q[0]) - ms.x) * ms.y * g0.x + b0.x; o[1] = (bfhi(q[0]) - ms.x) * ms.y * g0.y + b0.y;
;           o[2] = (bflo(q[1]) - ms.x) * ms.y * g0.z + b0.z; o[3] = (bfhi(q[1]) - ms.x) * ms.y * g0.w + b0.w;
;           o[4] = (bflo(q[2]) - ms.x) * ms.y * g1.x + b1.x; o[5] = (bfhi(q[2]) - ms.x) * ms.y * g1.y + b1.y;
;           o[6] = (bflo(q[3]) - ms.x) * ms.y * g1.z + b1.z; o[7] = (bfhi(q[3]) - ms.x) * ms.y * g1.w + b1.w;
;           if (c >= 128) {
;             float* dst = p.out + OUT_SGUV + ((size_t)(e * 16 + (c - 128)) * 32 + i) * 1024 + ch;
;             *(float4*)dst = make_float4(o[0], o[1], o[2], o[3]);
;             *(float4*)(dst + 4) = make_float4(o[4], o[5], o[6], o[7]);
;           }
.LBB0_1183:
	v_cmp_gt_i32_e64 s[48:49], s6, v86
	v_cmp_gt_i32_e64 s[46:47], s6, v92
	v_cmp_gt_i32_e64 s[44:45], s6, v94
	v_cndmask_b32_e64 v0, 0, v86, s[48:49]
	s_waitcnt lgkmcnt(0)
	v_cndmask_b32_e64 v2, 0, v92, s[46:47]
	v_cndmask_b32_e64 v4, 0, v94, s[44:45]
	v_cmp_gt_i32_e64 s[40:41], s6, v96
	v_add_u32_e32 v0, s5, v0
	v_add_u32_e32 v2, s5, v2
	v_add_u32_e32 v4, s5, v4
	v_cndmask_b32_e64 v6, 0, v96, s[40:41]
	s_and_b32 s98, s4, 7
	s_lshl_b32 s98, s98, 2
	s_bfe_u32 s99, s4, 0x20003
	s_or_b32 s98, s98, s99
	s_andn2_b32 s99, s4, 31
	s_or_b32 s98, s98, s99
	s_lshl_b32 s7, s98, 8
	v_ashrrev_i32_e32 v1, 31, v0
	v_readlane_b32 s10, v252, 33
	v_ashrrev_i32_e32 v3, 31, v2
	v_ashrrev_i32_e32 v5, 31, v4
	v_add_u32_e32 v6, s5, v6
	s_and_b32 s34, s7, 0x300
	v_lshlrev_b64 v[0:1], 12, v[0:1]
	v_readlane_b32 s11, v252, 34
	v_lshlrev_b64 v[2:3], 12, v[2:3]
	v_lshlrev_b64 v[4:5], 12, v[4:5]
	v_ashrrev_i32_e32 v7, 31, v6
	v_lshl_add_u64 v[0:1], s[10:11], 0, v[0:1]
	s_lshl_b32 s8, s34, 1
	s_mov_b32 s9, s35
	v_lshl_add_u64 v[2:3], s[10:11], 0, v[2:3]
	v_lshl_add_u64 v[4:5], s[10:11], 0, v[4:5]
	v_lshlrev_b64 v[6:7], 12, v[6:7]
	v_lshl_add_u64 v[0:1], v[0:1], 0, s[8:9]
	v_lshl_add_u64 v[2:3], v[2:3], 0, s[8:9]
	v_lshlrev_b32_e32 v182, 1, v88
	v_lshl_add_u64 v[4:5], v[4:5], 0, s[8:9]
	v_lshl_add_u64 v[6:7], s[10:11], 0, v[6:7]
	v_lshl_add_u64 v[2:3], v[2:3], 0, v[182:183]
	v_lshl_add_u64 v[4:5], v[4:5], 0, v[182:183]
	v_lshl_add_u64 v[6:7], v[6:7], 0, s[8:9]
	v_lshl_add_u64 v[116:117], v[0:1], 0, v[182:183]
	s_barrier
	v_lshl_add_u64 v[52:53], v[6:7], 0, v[182:183]
	global_load_dwordx4 v[44:47], v[116:117], off offset:2176
	global_load_dwordx4 v[28:31], v[116:117], off offset:2304
	global_load_dwordx4 v[40:43], v[2:3], off offset:2176
	global_load_dwordx4 v[24:27], v[2:3], off offset:2304
	global_load_dwordx4 v[36:39], v[4:5], off offset:2176
	global_load_dwordx4 v[20:23], v[4:5], off offset:2304
	global_load_dwordx4 v[32:35], v[52:53], off offset:2176
	global_load_dwordx4 v[16:19], v[52:53], off offset:2304
	global_load_dwordx4 v[72:75], v[2:3], off offset:2048
	global_load_dwordx4 v[12:15], v[116:117], off offset:2432
	global_load_dwordx4 v[68:71], v[4:5], off offset:2048
	global_load_dwordx4 v[8:11], v[2:3], off offset:2432
	global_load_dwordx4 v[48:51], v[52:53], off offset:2048
	s_nop 0
	global_load_dwordx4 v[4:7], v[4:5], off offset:2432
	s_nop 0
	global_load_dwordx4 v[0:3], v[52:53], off offset:2432
	v_or_b32_e32 v52, s34, v88
	v_readlane_b32 s8, v252, 8
	v_lshlrev_b32_e32 v182, 2, v52
	v_readlane_b32 s12, v252, 12
	v_readlane_b32 s13, v252, 13
	v_readlane_b32 s14, v252, 14
	v_readlane_b32 s15, v252, 15
	s_nop 2
	global_load_dwordx4 v[52:55], v182, s[12:13] offset:16
	s_nop 0
	global_load_dwordx4 v[56:59], v182, s[14:15] offset:16
	global_load_dwordx4 v[60:63], v182, s[12:13]
	global_load_dwordx4 v[64:67], v182, s[14:15]
	s_cmpk_gt_i32 s60, 0x7f
	v_readlane_b32 s9, v252, 9
	s_cselect_b64 s[6:7], -1, 0
	s_add_i32 s8, s60, 0xffffff80
	s_mov_b32 s9, s35
	v_cndmask_b32_e64 v77, 0, 1, s[6:7]
	s_lshl_b64 s[50:51], s[8:9], 17
	v_mov_b32_e32 v76, 0
	v_cmp_ne_u32_e64 s[42:43], 1, v77
	v_mov_b32_e32 v82, 0
	v_mov_b32_e32 v83, 0
	v_mov_b32_e32 v84, 0
	v_mov_b32_e32 v85, 0
	v_mov_b32_e32 v78, 0
	v_mov_b32_e32 v79, 0
	v_mov_b32_e32 v80, 0
	v_mov_b32_e32 v81, 0
	v_readlane_b32 s10, v252, 10
	v_readlane_b32 s11, v252, 11
	v_readlane_b32 s16, v252, 16
	v_readlane_b32 s17, v252, 17
	v_readlane_b32 s18, v252, 18
	v_readlane_b32 s19, v252, 19
	v_readlane_b32 s20, v252, 20
	v_readlane_b32 s21, v252, 21
	v_readlane_b32 s22, v252, 22
	v_readlane_b32 s23, v252, 23
	s_and_saveexec_b64 s[52:53], s[48:49]
	s_cbranch_execz .LBB0_1186
	global_load_dwordx4 v[78:81], v[116:117], off offset:2048
	ds_read_b64 v[82:83], v124
	s_and_b64 vcc, exec, s[42:43]
	s_waitcnt vmcnt(0)
	v_lshlrev_b32_e32 v84, 16, v78
	v_and_b32_e32 v85, 0xffff0000, v78
	v_lshlrev_b32_e32 v78, 16, v79
	v_and_b32_e32 v79, 0xffff0000, v79
	v_lshlrev_b32_e32 v116, 16, v80
	v_and_b32_e32 v117, 0xffff0000, v80
	v_lshlrev_b32_e32 v80, 16, v81
	v_and_b32_e32 v81, 0xffff0000, v81
	s_waitcnt lgkmcnt(0)
	v_pk_add_f32 v[84:85], v[84:85], v[82:83] op_sel_hi:[1,0] neg_lo:[0,1] neg_hi:[0,1]
	v_pk_add_f32 v[78:79], v[78:79], v[82:83] op_sel_hi:[1,0] neg_lo:[0,1] neg_hi:[0,1]
	v_pk_add_f32 v[116:117], v[116:117], v[82:83] op_sel_hi:[1,0] neg_lo:[0,1] neg_hi:[0,1]
	v_pk_add_f32 v[80:81], v[80:81], v[82:83] op_sel_hi:[1,0] neg_lo:[0,1] neg_hi:[0,1]
	v_pk_mul_f32 v[84:85], v[82:83], v[84:85] op_sel:[1,0]
	v_pk_mul_f32 v[78:79], v[82:83], v[78:79] op_sel:[1,0]
	v_pk_mul_f32 v[116:117], v[82:83], v[116:117] op_sel:[1,0]
	v_pk_mul_f32 v[80:81], v[82:83], v[80:81] op_sel:[1,0]
	v_pk_fma_f32 v[82:83], v[60:61], v[84:85], v[64:65]
	v_pk_fma_f32 v[84:85], v[62:63], v[78:79], v[66:67]
	v_pk_fma_f32 v[78:79], v[52:53], v[116:117], v[56:57]
	v_pk_fma_f32 v[80:81], v[54:55], v[80:81], v[58:59]
	s_cbranch_vccnz .LBB0_1186
	v_lshl_add_u64 v[116:117], v[106:107], 0, s[50:51]
	v_lshl_add_u64 v[116:117], v[116:117], 0, v[182:183]
	global_store_dwordx4 v[116:117], v[82:85], off
	global_store_dwordx4 v[116:117], v[78:81], off offset:16
